# NA loop: a wave skips the compute part of an iteration when neither the current nor the next key tile is inside its 8-row window (scores are all -inf there, contribution exactly zero); staging and bar
# speedup vs baseline: 1.0041x; 1.0018x over previous
; #define LAS __attribute__((address_space(3)))
; #define SBAR_() __builtin_amdgcn_sched_barrier(0)
; template <int MODE, bool FROZEN = false>
; __device__ __forceinline__ bool attn_unit(LAS unsigned char* lds, const Params& p, int l, int ua, int ub) {
;     ...
;         {
;             const size_t advk = (size_t)min(t + 3, NT - 1) * 64 * NPROJ, advv = (size_t)min(t + 2, NT - 1) * 64;
; #pragma unroll
;             for (int i = 0; i < NKC; ++i) kr[i] = *(const u32x4*)(kvbase + advk + ksrc[i]);
; #pragma unroll
;             for (int i = 0; i < NVC; ++i) vr[i] = *(const u32x4*)(vtbase + advv + vsrc[i]);
;         }
;         f32x16 sA0 = sB0, sA1 = sB1;
;         const float c2 = cbB - m_run;
;         const LAS unsigned char* Vb = lds + OFF_V + (t & 1) * VBUF + vlane_off;
;         const LAS unsigned char* Kb = lds + OFF_K + ((t + 1) & 1) * KBUF + klane_off;
;     ...
;         bf16x8 kf0[4], kf1[4], va[NB], vb[NB], pf0, pf1; float ps0, ps1, ps2, ps3;
;         VLOAD(0, va);
;         EXPCVT(0, pf0, ps0);
;         SBAR_();
;         VLOAD(1, vb); PVMMA(va, pf0); EXPCVT(1, pf1, ps1); _Pragma("unroll") for (int g_ = 0; g_ < NB; ++g_) { __builtin_amdgcn_sched_group_barrier(0x008, 1, 0); __builtin_amdgcn_sched_group_barrier(0x100, 1, 0); __builtin_amdgcn_sched_group_barrier(0x400, 8 / NB, 0); __builtin_amdgcn_sched_group_barrier(0x002, 12 / NB, 0); } SBAR_();
;         VLOAD(2, va);
; #pragma unroll
;         for (int d0 = 0; d0 < 4; ++d0) { kf0[d0] = *(const LAS bf16x8*)(Kb + d0 * 32); kf1[d0] = *(const LAS bf16x8*)(Kb + 32 * KPB + d0 * 32); }
;         PVMMA(vb, pf1); EXPCVT(2, pf0, ps2); _Pragma("unroll") for (int g_ = 0; g_ < NB; ++g_) { __builtin_amdgcn_sched_group_barrier(0x008, 1, 0); __builtin_amdgcn_sched_group_barrier(0x100, 1, 0); __builtin_amdgcn_sched_group_barrier(0x400, 8 / NB, 0); __builtin_amdgcn_sched_group_barrier(0x002, 12 / NB, 0); } SBAR_();
;         {
;             f32x16 z0, z1;
; #pragma unroll
;             for (int r = 0; r < 16; ++r) { z0[r] = 0.f; z1[r] = 0.f; }
; #pragma unroll
;             for (int d0 = 0; d0 < 4; ++d0) { z0 = __builtin_amdgcn_mfma_f32_32x32x16_bf16(kf0[d0], qf[d0], z0, 0, 0, 0); z1 = __builtin_amdgcn_mfma_f32_32x32x16_bf16(kf1[d0], qf[d0], z1, 0, 0, 0); }
;             sB0 = z0; sB1 = z1;
;         }
;         EXPCVT(3, pf1, ps3);
; #pragma unroll
.LBB0_264:
	s_add_i32 s12, s21, 3
	s_min_i32 vcc_lo, s12, s18
	s_min_i32 s12, s23, s18
	s_ashr_i32 s13, s12, 31
	s_lshl_b64 s[12:13], s[12:13], 7
	v_mad_i64_i32 v[68:69], vcc, vcc_lo, v243, v[126:127]
	v_lshl_add_u64 v[70:71], v[128:129], 0, s[12:13]
	global_load_dwordx4 v[120:123], v[68:69], off
	global_load_dwordx4 v[116:119], v[70:71], off
	s_add_i32 s100, s21, 1
	s_cmp_lt_i32 s100, s16
	s_cbranch_scc1 .LBB0_334
	s_cmp_gt_i32 s21, s8
	s_cbranch_scc1 .LBB0_334
	v_add_f32_e64 v35, -v152, v52
	v_exp_f32_e32 v84, v35
	v_add_f32_e64 v35, -v152, v53
	v_exp_f32_e32 v86, v35
	v_add_f32_e64 v35, -v152, v54
	v_exp_f32_e32 v138, v35
	v_add_f32_e64 v35, -v152, v55
	v_exp_f32_e32 v142, v35
	v_add_f32_e64 v35, -v152, v56
	v_exp_f32_e32 v134, v35
	v_add_f32_e64 v35, -v152, v57
	s_bitcmp1_b32 s21, 0
	v_exp_f32_e32 v140, v35
	v_add_f32_e64 v35, -v152, v58
	s_cselect_b32 s12, 0x2400, 0
	v_exp_f32_e32 v132, v35
	v_add_f32_e64 v35, -v152, v59
	v_add_u32_e32 v1, s12, v150
	v_exp_f32_e32 v136, v35
	ds_read_b128 v[68:71], v1 offset:18432
	ds_read_b128 v[72:75], v1 offset:23040
	v_cvt_pk_bf16_f32 v52, v84, v86
	v_cvt_pk_bf16_f32 v53, v138, v142
	v_cvt_pk_bf16_f32 v54, v134, v140
	v_cvt_pk_bf16_f32 v55, v132, v136
	s_waitcnt lgkmcnt(1)
	s_nop 0
	v_mfma_f32_32x32x16_bf16 v[2:17], v[68:71], v[52:55], v[2:17]
	ds_read_b128 v[56:59], v1 offset:18464
	v_add_f32_e64 v60, -v152, v60
	v_exp_f32_e32 v98, v60
	v_add_f32_e64 v61, -v152, v61
	v_exp_f32_e32 v96, v61
	v_add_f32_e64 v62, -v152, v62
	v_exp_f32_e32 v146, v62
	v_add_f32_e64 v35, -v152, v64
	v_exp_f32_e32 v90, v35
	v_add_f32_e64 v35, -v152, v65
	v_exp_f32_e32 v94, v35
	v_add_f32_e64 v35, -v152, v66
	v_exp_f32_e32 v88, v35
	v_add_f32_e64 v35, -v152, v67
	v_exp_f32_e32 v92, v35
	v_add_f32_e64 v35, -v152, v63
	v_exp_f32_e32 v144, v35
	v_cvt_pk_bf16_f32 v62, v90, v94
	v_cvt_pk_bf16_f32 v63, v88, v92
	v_cvt_pk_bf16_f32 v61, v146, v144
	s_waitcnt lgkmcnt(1)
	v_mfma_f32_32x32x16_bf16 v[18:33], v[72:75], v[52:55], v[18:33]
	ds_read_b128 v[52:55], v1 offset:23072
	v_cvt_pk_bf16_f32 v60, v98, v96
	v_add_u32_e32 v35, s22, v149
	s_waitcnt lgkmcnt(1)
	v_mfma_f32_32x32x16_bf16 v[2:17], v[56:59], v[60:63], v[2:17]
	ds_read_b128 v[72:75], v1 offset:18496
	v_add_f32_e64 v36, -v152, v36
	v_exp_f32_e32 v85, v36
	v_add_f32_e64 v36, -v152, v43
	v_exp_f32_e32 v137, v36
	v_add_f32_e64 v37, -v152, v37
	v_exp_f32_e32 v87, v37
	v_add_f32_e64 v37, -v152, v42
	v_exp_f32_e32 v133, v37
	v_add_f32_e64 v38, -v152, v38
	v_exp_f32_e32 v139, v38
	v_add_f32_e64 v38, -v152, v41
	v_exp_f32_e32 v141, v38
	v_add_f32_e64 v39, -v152, v39
	v_exp_f32_e32 v143, v39
	v_add_f32_e64 v39, -v152, v40
	v_exp_f32_e32 v135, v39
	v_cvt_pk_bf16_f32 v83, v133, v137
	ds_read_b128 v[36:39], v35 offset:4608
	ds_read_b128 v[56:59], v35 offset:4640
	v_cvt_pk_bf16_f32 v82, v135, v141
	s_waitcnt lgkmcnt(3)
	v_mfma_f32_32x32x16_bf16 v[18:33], v[52:55], v[60:63], v[18:33]
	ds_read_b128 v[52:55], v35
	ds_read_b128 v[60:63], v35 offset:4672
	ds_read_b128 v[64:67], v35 offset:4704
	ds_read_b128 v[68:71], v1 offset:23104
	ds_read_b128 v[154:157], v35 offset:32
	ds_read_b128 v[158:161], v35 offset:64
	ds_read_b128 v[162:165], v35 offset:96
	v_cvt_pk_bf16_f32 v80, v85, v87
	v_cvt_pk_bf16_f32 v81, v139, v143
	v_add_f32_e64 v35, -v152, v51
	v_exp_f32_e32 v93, v35
	v_add_f32_e64 v35, -v152, v44
	v_exp_f32_e32 v99, v35
	v_add_f32_e64 v35, -v152, v46
	v_exp_f32_e32 v147, v35
	v_add_f32_e64 v35, -v152, v50
	v_exp_f32_e32 v89, v35
	v_add_f32_e64 v40, -v152, v45
	v_add_f32_e64 v76, -v152, v47
	v_add_f32_e64 v78, -v152, v48
	v_exp_f32_e32 v97, v40
	v_add_f32_e64 v79, -v152, v49
	s_waitcnt lgkmcnt(8)
	v_mfma_f32_32x32x16_bf16 v[36:51], v[36:39], v[100:103], 0
	s_waitcnt lgkmcnt(7)
	v_mfma_f32_32x32x16_bf16 v[36:51], v[56:59], v[104:107], v[36:51]
	s_waitcnt lgkmcnt(5)
	v_mfma_f32_32x32x16_bf16 v[36:51], v[60:63], v[108:111], v[36:51]
	s_waitcnt lgkmcnt(4)
	v_mfma_f32_32x32x16_bf16 v[36:51], v[64:67], v[112:115], v[36:51]
	v_mfma_f32_32x32x16_bf16 v[52:67], v[52:55], v[100:103], 0
	s_waitcnt lgkmcnt(2)
	v_mfma_f32_32x32x16_bf16 v[52:67], v[154:157], v[104:107], v[52:67]
	s_waitcnt lgkmcnt(1)
	v_mfma_f32_32x32x16_bf16 v[52:67], v[158:161], v[108:111], v[52:67]
	v_exp_f32_e32 v145, v76
	v_cvt_pk_bf16_f32 v76, v99, v97
	v_cvt_pk_bf16_f32 v77, v147, v145
	v_exp_f32_e32 v91, v78
	v_exp_f32_e32 v95, v79
	s_waitcnt lgkmcnt(0)
	v_mfma_f32_32x32x16_bf16 v[52:67], v[162:165], v[112:115], v[52:67]
	v_cvt_pk_bf16_f32 v79, v89, v93
	v_cvt_pk_bf16_f32 v78, v91, v95
	ds_read_b128 v[154:157], v1 offset:18528
	ds_read_b128 v[158:161], v1 offset:23136
	v_mfma_f32_32x32x16_bf16 v[2:17], v[72:75], v[80:83], v[2:17]
	v_add_f32_e64 v72, v138, v142
	v_add_f32_e64 v73, v139, v143
	v_add_f32_e64 v74, v134, v140
	v_add_f32_e64 v75, v135, v141
	v_add_f32_e64 v132, v132, v136
	v_add_f32_e64 v133, v133, v137
	v_pk_add_f32 v[84:85], v[84:85], v[86:87]
	v_pk_add_f32 v[74:75], v[74:75], v[132:133]
	s_andn2_b64 vcc, exec, s[10:11]
	v_mfma_f32_32x32x16_bf16 v[18:33], v[68:71], v[80:83], v[18:33]
	v_add_f32_e64 v68, v84, v72
	v_add_f32_e64 v69, v85, v73
	v_add_f32_e64 v72, v90, v94
	v_add_f32_e64 v73, v91, v95
	v_add_f32_e64 v68, v68, v74
	v_add_f32_e64 v69, v69, v75
	v_pk_add_f32 v[74:75], v[88:89], v[92:93]
	v_pk_add_f32 v[70:71], v[146:147], v[144:145]
	v_pk_add_f32 v[72:73], v[72:73], v[74:75]
	v_pk_add_f32 v[74:75], v[98:99], v[96:97]
	s_waitcnt lgkmcnt(1)
	v_mfma_f32_32x32x16_bf16 v[2:17], v[154:157], v[76:79], v[2:17]
	v_add_f32_e64 v70, v74, v70
	v_add_f32_e64 v71, v75, v71
	v_add_f32_e64 v70, v70, v72
	v_add_f32_e64 v71, v71, v73
	v_add_f32_e64 v68, v68, v70
	v_add_f32_e64 v69, v69, v71
	v_add_f32_e32 v1, v68, v69
	s_waitcnt lgkmcnt(0)
	v_mfma_f32_32x32x16_bf16 v[18:33], v[158:161], v[76:79], v[18:33]
	v_add_f32_e32 v0, v0, v1
	s_cbranch_vccnz .LBB0_334
	s_cmp_lt_i32 s20, s16
	s_cselect_b64 s[10:11], -1, 0
	s_cmp_ge_i32 s21, s8
	s_cselect_b64 s[12:13], -1, 0
	s_or_b64 s[10:11], s[12:13], s[10:11]
	s_and_b64 vcc, exec, s[10:11]
	s_cbranch_vccnz .LBB0_331
	s_add_i32 s10, s19, s21
	s_max_i32 s10, s10, -7
	s_add_i32 s10, s10, 7
	s_min_u32 s10, s10, 14
	s_mulk_i32 s10, 0x1fc
	v_add_u32_e32 v1, s10, v151
	v_mov_b32_e32 v35, 0xf149f2ca
	ds_read_b32 v68, v1 offset:36864
	ds_read_b32 v69, v1 offset:36992
	ds_read_b32 v70, v1 offset:36868
	ds_read_b32 v71, v1 offset:36996
	ds_read_b32 v72, v1 offset:36872
	ds_read_b32 v73, v1 offset:37000
	ds_read_b32 v74, v1 offset:36876
	ds_read_b32 v75, v1 offset:37004
	ds_read_b32 v76, v1 offset:36896
	ds_read_b32 v77, v1 offset:37024
	ds_read_b32 v78, v1 offset:36900
	ds_read_b32 v79, v1 offset:37028
	ds_read_b32 v80, v1 offset:36904
	ds_read_b32 v81, v1 offset:37032
	ds_read_b32 v82, v1 offset:36908
	s_waitcnt lgkmcnt(14)
	v_add_f32_e32 v68, v52, v68
	ds_read_b32 v83, v1 offset:37036
	v_cndmask_b32_e64 v52, v35, v68, s[38:39]
	s_waitcnt lgkmcnt(14)
	v_add_f32_e32 v69, v36, v69
	ds_read_b32 v84, v1 offset:36928
	v_cndmask_b32_e64 v36, v35, v69, s[40:41]
	s_waitcnt lgkmcnt(14)
	v_add_f32_e32 v70, v53, v70
	ds_read_b32 v85, v1 offset:37056
	v_cndmask_b32_e64 v53, v35, v70, s[42:43]
	s_waitcnt lgkmcnt(14)
	v_add_f32_e32 v71, v37, v71
	ds_read_b32 v86, v1 offset:36932
	v_cndmask_b32_e64 v37, v35, v71, s[44:45]
	s_waitcnt lgkmcnt(14)
	v_add_f32_e32 v72, v54, v72
	ds_read_b32 v87, v1 offset:37060
	v_cndmask_b32_e64 v54, v35, v72, s[46:47]
	s_waitcnt lgkmcnt(14)
	v_add_f32_e32 v73, v38, v73
	ds_read_b32 v88, v1 offset:36936
	v_cndmask_b32_e64 v38, v35, v73, s[48:49]
	s_waitcnt lgkmcnt(14)
	v_add_f32_e32 v74, v55, v74
	ds_read_b32 v89, v1 offset:37064
	v_cndmask_b32_e64 v55, v35, v74, s[50:51]
	s_waitcnt lgkmcnt(14)
	v_add_f32_e32 v75, v39, v75
	ds_read_b32 v90, v1 offset:36940
	v_cndmask_b32_e64 v39, v35, v75, s[52:53]
	s_waitcnt lgkmcnt(14)
	v_add_f32_e32 v76, v56, v76
	ds_read_b32 v91, v1 offset:37068
	v_cndmask_b32_e64 v56, v35, v76, s[54:55]
	s_waitcnt lgkmcnt(14)
	v_add_f32_e32 v77, v40, v77
	ds_read_b32 v92, v1 offset:36960
	v_cndmask_b32_e64 v40, v35, v77, s[56:57]
	s_waitcnt lgkmcnt(14)
	v_add_f32_e32 v78, v57, v78
	ds_read_b32 v93, v1 offset:37088
	v_cndmask_b32_e64 v57, v35, v78, s[58:59]
	s_waitcnt lgkmcnt(14)
	v_add_f32_e32 v79, v41, v79
	ds_read_b32 v94, v1 offset:36964
	v_cndmask_b32_e64 v41, v35, v79, s[60:61]
	s_waitcnt lgkmcnt(14)
	v_add_f32_e32 v80, v58, v80
	ds_read_b32 v95, v1 offset:37092
	v_cndmask_b32_e64 v58, v35, v80, s[62:63]
	s_waitcnt lgkmcnt(14)
	v_add_f32_e32 v81, v42, v81
	ds_read_b32 v96, v1 offset:36968
	v_cndmask_b32_e64 v42, v35, v81, s[64:65]
	s_waitcnt lgkmcnt(14)
	v_add_f32_e32 v82, v59, v82
	ds_read_b32 v97, v1 offset:37096
	v_cndmask_b32_e64 v59, v35, v82, s[66:67]
	s_waitcnt lgkmcnt(14)
	v_add_f32_e32 v83, v43, v83
	ds_read_b32 v98, v1 offset:36972
	v_cndmask_b32_e64 v43, v35, v83, s[68:69]
	s_waitcnt lgkmcnt(14)
	v_add_f32_e32 v84, v60, v84
	ds_read_b32 v99, v1 offset:37100
	v_cndmask_b32_e64 v60, v35, v84, s[70:71]
	s_waitcnt lgkmcnt(14)
	v_add_f32_e32 v85, v44, v85
	v_cndmask_b32_e64 v44, v35, v85, s[72:73]
	s_waitcnt lgkmcnt(13)
	v_add_f32_e32 v86, v61, v86
	v_cndmask_b32_e64 v61, v35, v86, s[74:75]
	s_waitcnt lgkmcnt(12)
	v_add_f32_e32 v87, v45, v87
	v_cndmask_b32_e64 v45, v35, v87, s[76:77]
	s_waitcnt lgkmcnt(11)
	v_add_f32_e32 v88, v62, v88
	v_cndmask_b32_e64 v62, v35, v88, s[78:79]
	s_waitcnt lgkmcnt(10)
	v_add_f32_e32 v89, v46, v89
	v_cndmask_b32_e64 v46, v35, v89, s[80:81]
	s_waitcnt lgkmcnt(9)
	v_add_f32_e32 v90, v63, v90
	v_cndmask_b32_e64 v63, v35, v90, s[82:83]
	s_waitcnt lgkmcnt(8)
	v_add_f32_e32 v91, v47, v91
	v_cndmask_b32_e64 v47, v35, v91, s[84:85]
	s_waitcnt lgkmcnt(7)
	v_add_f32_e32 v92, v64, v92
	v_cndmask_b32_e64 v64, v35, v92, s[86:87]
	s_waitcnt lgkmcnt(6)
	v_add_f32_e32 v93, v48, v93
	v_cndmask_b32_e64 v48, v35, v93, s[88:89]
	s_waitcnt lgkmcnt(5)
	v_add_f32_e32 v94, v65, v94
	v_cndmask_b32_e64 v65, v35, v94, s[90:91]
	s_waitcnt lgkmcnt(4)
	v_add_f32_e32 v95, v49, v95
	v_cndmask_b32_e64 v49, v35, v95, s[92:93]
	s_waitcnt lgkmcnt(3)
	v_add_f32_e32 v96, v66, v96
	v_cndmask_b32_e64 v66, v35, v96, s[94:95]
	s_waitcnt lgkmcnt(2)
	v_add_f32_e32 v97, v50, v97
	v_cndmask_b32_e64 v50, v35, v97, s[96:97]
	s_waitcnt lgkmcnt(1)
	v_add_f32_e32 v98, v67, v98
	v_cndmask_b32_e64 v67, v35, v98, s[0:1]
	s_waitcnt lgkmcnt(0)
	v_add_f32_e32 v99, v51, v99
	v_cndmask_b32_e64 v51, v35, v99, s[4:5]
	s_branch .LBB0_332
